# SSD prompt unit: DPP 16-lane sums instead of ds_bpermute butterflies, on top of batched LDS reads and counted prefetch wait
# speedup vs baseline: 1.0133x; 1.0023x over previous
.LBB0_368:
	v_add_u32_e32 v218, v128, v132
	ds_read_b128 v[74:77], v218
	ds_read_b128 v[220:223], v203
	ds_read_b128 v[78:81], v218 offset:64
	ds_read_b128 v[224:227], v203 offset:64
	ds_read_b128 v[228:231], v218 offset:128
	ds_read_b128 v[232:235], v203 offset:128
	ds_read_b128 v[236:239], v218 offset:192
	s_waitcnt lgkmcnt(6)
	v_mfma_f32_16x16x32_bf16 v[74:77], v[66:69], v[74:77], 0
	s_waitcnt lgkmcnt(5)
	v_mfma_f32_16x16x32_bf16 v[220:223], v[66:69], v[220:223], 0
	ds_read_b128 v[66:69], v203 offset:192
	s_waitcnt lgkmcnt(5)
	v_mfma_f32_16x16x32_bf16 v[74:77], v[62:65], v[78:81], v[74:77]
	s_waitcnt lgkmcnt(4)
	v_mfma_f32_16x16x32_bf16 v[220:223], v[62:65], v[224:227], v[220:223]
	s_waitcnt lgkmcnt(3)
	v_mfma_f32_16x16x32_bf16 v[74:77], v[58:61], v[228:231], v[74:77]
	s_waitcnt lgkmcnt(2)
	v_mfma_f32_16x16x32_bf16 v[220:223], v[58:61], v[232:235], v[220:223]
	s_waitcnt lgkmcnt(1)
	v_mfma_f32_16x16x32_bf16 v[74:77], v[70:73], v[236:239], v[74:77]
	s_waitcnt lgkmcnt(0)
	v_mfma_f32_16x16x32_bf16 v[58:61], v[70:73], v[66:69], v[220:223]
	s_waitcnt vmcnt(9)
	v_and_b32_e32 v63, 64, v204
	v_xor_b32_e32 v62, 1, v204
	v_add_u32_e32 v63, 64, v63
	v_cmp_lt_i32_e32 vcc, v62, v63
	s_nop 1
	v_cndmask_b32_e32 v62, v204, v62, vcc
	v_lshlrev_b32_e32 v64, 2, v62
	v_xor_b32_e32 v62, 2, v204
	v_cmp_lt_i32_e32 vcc, v62, v63
	s_nop 1
	v_cndmask_b32_e32 v62, v204, v62, vcc
	v_lshlrev_b32_e32 v66, 2, v62
	v_xor_b32_e32 v62, 4, v204
	v_cmp_lt_i32_e32 vcc, v62, v63
	s_nop 1
	v_cndmask_b32_e32 v62, v204, v62, vcc
	v_lshlrev_b32_e32 v67, 2, v62
	v_xor_b32_e32 v62, 8, v204
	v_cmp_lt_i32_e32 vcc, v62, v63
	s_nop 1
	v_cndmask_b32_e32 v62, v204, v62, vcc
	v_lshlrev_b32_e32 v65, 2, v62
	ds_read_b32 v62, v166
	ds_read_u16 v68, v167
	ds_read_u16 v73, v167 offset:32
	s_waitcnt lgkmcnt(2)
	v_mul_f32_e32 v62, 0x3fb8aa3b, v62
	v_exp_f32_e32 v72, v62
	s_waitcnt lgkmcnt(1)
	v_lshlrev_b32_e32 v68, 16, v68
	v_add_u32_e32 v62, -3, v118
	v_ashrrev_i32_e32 v63, 31, v62
	v_fma_f32 v54, v74, v72, v54
	v_fmac_f32_e32 v54, v208, v68
	v_lshlrev_b32_e32 v68, 16, v217
	v_mul_f32_e32 v69, 0xbfb8aa3b, v68
	v_exp_f32_e32 v69, v69
	v_fma_f32 v50, v58, v72, v50
	v_lshlrev_b32_e32 v58, 16, v216
	v_add_f32_e32 v69, 1.0, v69
	v_rcp_f32_e32 v69, v69
	s_nop 0
	v_mul_f32_e32 v68, v69, v68
	v_mul_f32_e32 v54, v68, v54
	v_lshlrev_b64 v[68:69], 12, v[62:63]
	v_lshl_or_b32 v68, s94, 1, v68
	v_cvt_pk_bf16_f32 v74, v54, s0
	v_lshl_add_u64 v[70:71], v[98:99], 0, v[68:69]
	global_store_short v[70:71], v74, off
	s_waitcnt lgkmcnt(0)
	v_lshlrev_b32_e32 v70, 16, v73
	v_fmac_f32_e32 v50, v208, v70
	v_mul_f32_e32 v70, 0xbfb8aa3b, v58
	v_exp_f32_e32 v70, v70
	v_lshl_add_u64 v[68:69], v[116:117], 0, v[68:69]
	v_add_f32_e32 v70, 1.0, v70
	v_rcp_f32_e32 v70, v70
	s_nop 0
	v_mul_f32_e32 v58, v70, v58
	v_mul_f32_e32 v50, v58, v50
	v_mul_f32_e32 v58, v50, v50
	v_fmac_f32_e32 v58, v54, v54
	v_cvt_pk_bf16_f32 v50, v50, s0
	global_store_short v[68:69], v50, off
	s_waitcnt lgkmcnt(0)
	s_nop 1
	v_add_f32_dpp v50, v58, v58 quad_perm:[1,0,3,2] row_mask:0xf bank_mask:0xf
	s_waitcnt lgkmcnt(0)
	s_nop 1
	v_add_f32_dpp v50, v50, v50 quad_perm:[2,3,0,1] row_mask:0xf bank_mask:0xf
	s_waitcnt lgkmcnt(0)
	s_nop 1
	v_add_f32_dpp v50, v50, v50 row_half_mirror row_mask:0xf bank_mask:0xf
	s_nop 1
	v_add_f32_dpp v54, v50, v50 row_mirror row_mask:0xf bank_mask:0xf
	s_and_saveexec_b64 s[24:25], s[4:5]
	s_cbranch_execz .LBB0_370
	v_lshlrev_b64 v[62:63], 8, v[62:63]
	s_waitcnt lgkmcnt(0)
	v_mov_b32_e32 v50, v54
	v_lshl_add_u64 v[62:63], s[88:89], 0, v[62:63]
	global_store_dword v[62:63], v50, off
.LBB0_370:
	s_or_b64 exec, exec, s[24:25]
	v_lshlrev_b32_e32 v62, 16, v215
	v_mul_f32_e32 v63, 0xbfb8aa3b, v62
	ds_read_b32 v50, v168
	s_waitcnt lgkmcnt(1)
	ds_read_u16 v54, v169
	ds_read_u16 v58, v169 offset:32
	v_exp_f32_e32 v63, v63
	v_lshlrev_b32_e32 v68, 16, v214
	s_waitcnt lgkmcnt(2)
	v_mul_f32_e32 v50, 0x3fb8aa3b, v50
	v_exp_f32_e32 v50, v50
	v_add_f32_e32 v63, 1.0, v63
	v_rcp_f32_e32 v63, v63
	v_mul_f32_e32 v69, 0xbfb8aa3b, v68
	v_exp_f32_e32 v69, v69
	s_waitcnt lgkmcnt(1)
	v_lshlrev_b32_e32 v54, 16, v54
	v_fma_f32 v55, v75, v50, v55
	v_fmac_f32_e32 v55, v208, v54
	v_mul_f32_e32 v54, v63, v62
	v_mul_f32_e32 v54, v54, v55
	v_add_f32_e32 v55, 1.0, v69
	v_rcp_f32_e32 v55, v55
	s_waitcnt lgkmcnt(0)
	v_lshlrev_b32_e32 v58, 16, v58
	v_fma_f32 v50, v59, v50, v51
	v_fmac_f32_e32 v50, v208, v58
	v_mul_f32_e32 v51, v55, v68
	v_mul_f32_e32 v68, v51, v50
	v_mul_f32_e32 v50, v68, v68
	v_fmac_f32_e32 v50, v54, v54
	v_cvt_pk_bf16_f32 v70, v54, s0
	s_waitcnt lgkmcnt(0)
	s_nop 1
	v_add_f32_dpp v55, v50, v50 quad_perm:[1,0,3,2] row_mask:0xf bank_mask:0xf
	v_add_u32_e32 v50, -2, v118
	v_ashrrev_i32_e32 v51, 31, v50
	s_waitcnt lgkmcnt(0)
	s_nop 1
	v_add_f32_dpp v55, v55, v55 quad_perm:[2,3,0,1] row_mask:0xf bank_mask:0xf
	v_lshlrev_b64 v[58:59], 12, v[50:51]
	v_lshl_or_b32 v58, s94, 1, v58
	v_lshl_add_u64 v[62:63], v[98:99], 0, v[58:59]
	global_store_short v[62:63], v70, off
	s_waitcnt lgkmcnt(0)
	s_nop 1
	v_add_f32_dpp v54, v55, v55 row_half_mirror row_mask:0xf bank_mask:0xf
	s_nop 1
	v_add_f32_dpp v55, v54, v54 row_mirror row_mask:0xf bank_mask:0xf
	v_cvt_pk_bf16_f32 v62, v68, s0
	v_lshl_add_u64 v[58:59], v[116:117], 0, v[58:59]
	global_store_short v[58:59], v62, off
	s_and_saveexec_b64 s[24:25], s[4:5]
	s_cbranch_execz .LBB0_372
	v_lshlrev_b64 v[50:51], 8, v[50:51]
	s_waitcnt lgkmcnt(0)
	v_mov_b32_e32 v54, v55
	v_lshl_add_u64 v[50:51], s[88:89], 0, v[50:51]
	global_store_dword v[50:51], v54, off
.LBB0_372:
	s_or_b64 exec, exec, s[24:25]
	s_waitcnt lgkmcnt(0)
	v_lshlrev_b32_e32 v55, 16, v213
	v_mul_f32_e32 v58, 0xbfb8aa3b, v55
	ds_read_b32 v50, v170
	ds_read_u16 v51, v171
	ds_read_u16 v54, v171 offset:32
	v_exp_f32_e32 v58, v58
	v_lshlrev_b32_e32 v59, 16, v212
	s_waitcnt lgkmcnt(2)
	v_mul_f32_e32 v50, 0x3fb8aa3b, v50
	v_exp_f32_e32 v50, v50
	v_add_f32_e32 v58, 1.0, v58
	v_rcp_f32_e32 v58, v58
	v_mul_f32_e32 v62, 0xbfb8aa3b, v59
	v_exp_f32_e32 v62, v62
	s_waitcnt lgkmcnt(1)
	v_lshlrev_b32_e32 v51, 16, v51
	v_fma_f32 v56, v76, v50, v56
	v_fmac_f32_e32 v56, v208, v51
	v_mul_f32_e32 v51, v58, v55
	v_mul_f32_e32 v55, v51, v56
	v_add_f32_e32 v51, 1.0, v62
	v_rcp_f32_e32 v51, v51
	s_waitcnt lgkmcnt(0)
	v_lshlrev_b32_e32 v54, 16, v54
	v_fma_f32 v50, v60, v50, v52
	v_fmac_f32_e32 v50, v208, v54
	v_mul_f32_e32 v51, v51, v59
	v_mul_f32_e32 v56, v51, v50
	v_mul_f32_e32 v50, v56, v56
	v_fmac_f32_e32 v50, v55, v55
	v_cvt_pk_bf16_f32 v55, v55, s0
	s_waitcnt lgkmcnt(0)
	s_nop 1
	v_add_f32_dpp v52, v50, v50 quad_perm:[1,0,3,2] row_mask:0xf bank_mask:0xf
	v_add_u32_e32 v50, -1, v118
	v_ashrrev_i32_e32 v51, 31, v50
	v_lshlrev_b64 v[58:59], 12, v[50:51]
	v_lshl_or_b32 v58, s94, 1, v58
	s_waitcnt lgkmcnt(0)
	s_nop 1
	v_add_f32_dpp v52, v52, v52 quad_perm:[2,3,0,1] row_mask:0xf bank_mask:0xf
	v_lshl_add_u64 v[62:63], v[98:99], 0, v[58:59]
	global_store_short v[62:63], v55, off
	v_cvt_pk_bf16_f32 v55, v56, s0
	v_lshl_add_u64 v[58:59], v[116:117], 0, v[58:59]
	s_waitcnt lgkmcnt(0)
	s_nop 1
	v_add_f32_dpp v52, v52, v52 row_half_mirror row_mask:0xf bank_mask:0xf
	s_nop 1
	v_add_f32_dpp v54, v52, v52 row_mirror row_mask:0xf bank_mask:0xf
	global_store_short v[58:59], v55, off
	s_and_saveexec_b64 s[24:25], s[4:5]
	s_cbranch_execz .LBB0_374
	v_lshlrev_b64 v[50:51], 8, v[50:51]
	s_waitcnt lgkmcnt(0)
	v_mov_b32_e32 v52, v54
	v_lshl_add_u64 v[50:51], s[88:89], 0, v[50:51]
	global_store_dword v[50:51], v52, off
.LBB0_374:
	s_or_b64 exec, exec, s[24:25]
	s_waitcnt lgkmcnt(0)
	v_lshlrev_b32_e32 v54, 16, v119
	v_mul_f32_e32 v55, 0xbfb8aa3b, v54
	ds_read_b32 v50, v173
	ds_read_u16 v51, v175
	ds_read_u16 v52, v175 offset:32
	v_exp_f32_e32 v55, v55
	v_lshlrev_b32_e32 v56, 16, v97
	s_waitcnt lgkmcnt(2)
	v_mul_f32_e32 v50, 0x3fb8aa3b, v50
	v_exp_f32_e32 v50, v50
	v_add_f32_e32 v55, 1.0, v55
	v_mul_f32_e32 v58, 0xbfb8aa3b, v56
	v_rcp_f32_e32 v55, v55
	v_exp_f32_e32 v58, v58
	s_waitcnt lgkmcnt(1)
	v_lshlrev_b32_e32 v51, 16, v51
	v_fmac_f32_e32 v57, v77, v50
	v_fmac_f32_e32 v57, v208, v51
	v_mul_f32_e32 v51, v55, v54
	v_add_f32_e32 v54, 1.0, v58
	v_rcp_f32_e32 v54, v54
	s_waitcnt lgkmcnt(0)
	v_lshlrev_b32_e32 v52, 16, v52
	v_fmac_f32_e32 v53, v61, v50
	v_fmac_f32_e32 v53, v208, v52
	v_mul_f32_e32 v50, v54, v56
	v_mul_f32_e32 v56, v50, v53
	v_mul_f32_e32 v51, v51, v57
	v_mul_f32_e32 v50, v56, v56
	v_fmac_f32_e32 v50, v51, v51
	v_ashrrev_i32_e32 v119, 31, v118
	v_cvt_pk_bf16_f32 v58, v51, s0
	s_waitcnt lgkmcnt(0)
	s_nop 1
	v_add_f32_dpp v50, v50, v50 quad_perm:[1,0,3,2] row_mask:0xf bank_mask:0xf
	s_waitcnt lgkmcnt(0)
	s_nop 1
	v_add_f32_dpp v50, v50, v50 quad_perm:[2,3,0,1] row_mask:0xf bank_mask:0xf
	v_lshlrev_b64 v[52:53], 12, v[118:119]
	v_lshl_or_b32 v52, s94, 1, v52
	v_lshl_add_u64 v[54:55], v[98:99], 0, v[52:53]
	global_store_short v[54:55], v58, off
	s_waitcnt lgkmcnt(0)
	s_nop 1
	v_add_f32_dpp v50, v50, v50 row_half_mirror row_mask:0xf bank_mask:0xf
	s_nop 1
	v_add_f32_dpp v51, v50, v50 row_mirror row_mask:0xf bank_mask:0xf
	v_cvt_pk_bf16_f32 v54, v56, s0
	v_lshl_add_u64 v[52:53], v[116:117], 0, v[52:53]
	global_store_short v[52:53], v54, off
	s_and_saveexec_b64 s[24:25], s[4:5]
	s_cbranch_execz .LBB0_376
	s_waitcnt lgkmcnt(0)
	v_mov_b32_e32 v52, v51
	v_lshlrev_b64 v[50:51], 8, v[118:119]
	v_lshl_add_u64 v[50:51], s[88:89], 0, v[50:51]
	global_store_dword v[50:51], v52, off
